# first K-iteration of non-first tiles peeled with relaxed counted waits (epilogue stores stay in flight); P1+P5 epilogue row-scale prefetch; P2a slot rotation
# speedup vs baseline: 1.0087x; 1.0048x over previous
;     __device__ __forceinline__ const char* a(const Unit& u) const { return (const char*)A + (size_t)u.pm * 2 * hA(); }
;     __device__ __forceinline__ const char* b(const Unit& u) const { return (const char*)Bt + (size_t)u.pn * 2 * hB() + (size_t)(u.pm >> gshift) * goff; }
;     __device__ __forceinline__ const char* a(const Unit& u) const { return (const char*)A + (size_t)u.pm * 2 * hA(); }
;     __device__ __forceinline__ const char* b(const Unit& u) const { return (const char*)Bt + (size_t)((u.pn >> 4) * 4096 + (u.pn & 15) * 16) * 1024 * 2 + (size_t)(u.pm >> 1) * 512; }
;     __device__ __forceinline__ const char* a(const Unit&) const { return (const char*)A; }
;     __device__ __forceinline__ const char* b(const Unit& u) const { return (const char*)Bt + ((size_t)(((u.pm >> 4) * 1024 + u.pn * 256) * 16 + (u.pm & 15)) * 512) * 2; }
;     ...
; #pragma unroll
;         for (int a = 0; a < 2; ++a)
; #pragma unroll
;             for (int b = 0; b < 2; ++b)
; #pragma unroll
;                 for (int m = 0; m < 4; ++m)
; #pragma unroll
;                     for (int n = 0; n < 2; ++n) acc[a][b][m][n] = (f32x4){0.f, 0.f, 0.f, 0.f};
;         cur = nxt; cA = nA; cB = nB; ++ui;
.LBB0_181:
	s_ashr_i32 s21, s20, 31
	s_lshl_b64 s[22:23], s[20:21], 20
	v_readlane_b32 s26, v254, 20
	v_readlane_b32 s27, v254, 21
	s_add_u32 s22, s26, s22
	s_addc_u32 s23, s27, s23
	s_and_b64 s[26:27], s[8:9], exec
	s_cselect_b32 s5, s23, s29
	s_cselect_b32 s7, s22, s28
	s_ashr_i32 s19, s18, 31
	s_lshl_b64 s[26:27], s[18:19], 20
	s_add_u32 s26, s24, s26
	s_addc_u32 s27, s25, s27
	s_and_b64 s[34:35], s[8:9], exec
	s_cselect_b32 s19, s27, s31
	s_cselect_b32 s21, s26, s30
	s_add_u32 s61, s30, 0x100
	v_mov_b32_e32 v0, 0
	s_addc_u32 s66, s31, 0
	s_mov_b32 s67, -2
	v_mov_b32_e32 v1, v0
	v_mov_b32_e32 v2, v0
	v_mov_b32_e32 v3, v0
	v_mov_b32_e32 v4, v0
	v_mov_b32_e32 v5, v0
	v_mov_b32_e32 v6, v0
	v_mov_b32_e32 v7, v0
	v_mov_b32_e32 v16, v0
	v_mov_b32_e32 v17, v0
	v_mov_b32_e32 v18, v0
	v_mov_b32_e32 v19, v0
	v_mov_b32_e32 v20, v0
	v_mov_b32_e32 v21, v0
	v_mov_b32_e32 v22, v0
	v_mov_b32_e32 v23, v0
	v_mov_b32_e32 v32, v0
	v_mov_b32_e32 v33, v0
	v_mov_b32_e32 v34, v0
	v_mov_b32_e32 v35, v0
	v_mov_b32_e32 v36, v0
	v_mov_b32_e32 v37, v0
	v_mov_b32_e32 v38, v0
	v_mov_b32_e32 v39, v0
	v_mov_b32_e32 v48, v0
	v_mov_b32_e32 v49, v0
	v_mov_b32_e32 v50, v0
	v_mov_b32_e32 v51, v0
	v_mov_b32_e32 v52, v0
	v_mov_b32_e32 v53, v0
	v_mov_b32_e32 v54, v0
	v_mov_b32_e32 v55, v0
	v_mov_b32_e32 v8, v0
	v_mov_b32_e32 v9, v0
	v_mov_b32_e32 v10, v0
	v_mov_b32_e32 v11, v0
	v_mov_b32_e32 v12, v0
	v_mov_b32_e32 v13, v0
	v_mov_b32_e32 v14, v0
	v_mov_b32_e32 v15, v0
	v_mov_b32_e32 v24, v0
	v_mov_b32_e32 v25, v0
	v_mov_b32_e32 v26, v0
	v_mov_b32_e32 v27, v0
	v_mov_b32_e32 v28, v0
	v_mov_b32_e32 v29, v0
	v_mov_b32_e32 v30, v0
	v_mov_b32_e32 v31, v0
	v_mov_b32_e32 v40, v0
	v_mov_b32_e32 v41, v0
	v_mov_b32_e32 v42, v0
	v_mov_b32_e32 v43, v0
	v_mov_b32_e32 v44, v0
	v_mov_b32_e32 v45, v0
	v_mov_b32_e32 v46, v0
	v_mov_b32_e32 v47, v0
	v_mov_b32_e32 v56, v0
	v_mov_b32_e32 v57, v0
	v_mov_b32_e32 v58, v0
	v_mov_b32_e32 v59, v0
	v_mov_b32_e32 v60, v0
	v_mov_b32_e32 v61, v0
	v_mov_b32_e32 v62, v0
	v_mov_b32_e32 v63, v0
	v_mov_b32_e32 v64, v0
	v_mov_b32_e32 v65, v0
	v_mov_b32_e32 v66, v0
	v_mov_b32_e32 v67, v0
	v_mov_b32_e32 v68, v0
	v_mov_b32_e32 v69, v0
	v_mov_b32_e32 v70, v0
	v_mov_b32_e32 v71, v0
	v_mov_b32_e32 v80, v0
	v_mov_b32_e32 v81, v0
	v_mov_b32_e32 v82, v0
	v_mov_b32_e32 v83, v0
	v_mov_b32_e32 v84, v0
	v_mov_b32_e32 v85, v0
	v_mov_b32_e32 v86, v0
	v_mov_b32_e32 v87, v0
	v_mov_b32_e32 v96, v0
	v_mov_b32_e32 v97, v0
	v_mov_b32_e32 v98, v0
	v_mov_b32_e32 v99, v0
	v_mov_b32_e32 v100, v0
	v_mov_b32_e32 v101, v0
	v_mov_b32_e32 v102, v0
	v_mov_b32_e32 v103, v0
	v_mov_b32_e32 v112, v0
	v_mov_b32_e32 v113, v0
	v_mov_b32_e32 v114, v0
	v_mov_b32_e32 v115, v0
	v_mov_b32_e32 v116, v0
	v_mov_b32_e32 v117, v0
	v_mov_b32_e32 v118, v0
	v_mov_b32_e32 v119, v0
	v_mov_b32_e32 v72, v0
	v_mov_b32_e32 v73, v0
	v_mov_b32_e32 v74, v0
	v_mov_b32_e32 v75, v0
	v_mov_b32_e32 v76, v0
	v_mov_b32_e32 v77, v0
	v_mov_b32_e32 v78, v0
	v_mov_b32_e32 v79, v0
	v_mov_b32_e32 v88, v0
	v_mov_b32_e32 v89, v0
	v_mov_b32_e32 v90, v0
	v_mov_b32_e32 v91, v0
	v_mov_b32_e32 v92, v0
	v_mov_b32_e32 v93, v0
	v_mov_b32_e32 v94, v0
	v_mov_b32_e32 v95, v0
	v_mov_b32_e32 v104, v0
	v_mov_b32_e32 v105, v0
	v_mov_b32_e32 v106, v0
	v_mov_b32_e32 v107, v0
	v_mov_b32_e32 v108, v0
	v_mov_b32_e32 v109, v0
	v_mov_b32_e32 v110, v0
	v_mov_b32_e32 v111, v0
	v_mov_b32_e32 v120, v0
	v_mov_b32_e32 v121, v0
	v_mov_b32_e32 v122, v0
	v_mov_b32_e32 v123, v0
	v_mov_b32_e32 v124, v0
	v_mov_b32_e32 v125, v0
	v_mov_b32_e32 v126, v0
	v_mov_b32_e32 v127, v0
	s_cmp_lt_u32 s54, 2
	s_cbranch_scc1 .LBB0_182
	s_add_u32 s30, s28, 0x100
	s_addc_u32 s31, s29, 0
	s_cmp_eq_u32 s67, 28
	s_cselect_b32 s42, s7, s30
	s_cselect_b32 s43, s5, s31
	s_cselect_b32 s45, s19, s66
	s_cselect_b32 s44, s21, s61
	s_add_u32 s34, s42, 0x80
	s_addc_u32 s35, s43, 0
	s_add_u32 s36, s44, 0x80
	s_addc_u32 s37, s45, 0
	s_add_u32 s68, s28, 0x80080
	s_addc_u32 s69, s29, 0
	s_add_u32 s40, s42, 0x80000
	s_addc_u32 s41, s43, 0
	s_add_u32 s46, s44, 0x80000
	s_addc_u32 s47, s45, 0
	s_add_u32 s28, s44, 0x80080
	s_addc_u32 s29, s45, 0
	ds_read_b128 v[140:143], v133
	ds_read_b128 v[144:147], v133 offset:1024
	ds_read_b128 v[148:151], v133 offset:2048
	ds_read_b128 v[152:155], v133 offset:3072
	ds_read_b128 v[156:159], v135
	ds_read_b128 v[160:163], v135 offset:1024
	ds_read_b128 v[168:171], v135 offset:2048
	ds_read_b128 v[172:175], v135 offset:3072
	s_add_i32 m0, s38, 0xc000
	ds_read_b128 v[176:179], v164
	ds_read_b128 v[180:183], v164 offset:1024
	ds_read_b128 v[184:187], v164 offset:2048
	ds_read_b128 v[188:191], v164 offset:3072
	ds_read_b128 v[192:195], v164 offset:4096
	ds_read_b128 v[196:199], v164 offset:5120
	ds_read_b128 v[200:203], v164 offset:6144
	ds_read_b128 v[204:207], v164 offset:7168
	global_load_lds_dwordx4 v128, s[68:69]
	s_add_i32 m0, s38, 0xe000
	s_nop 0
	global_load_lds_dwordx4 v132, s[68:69]
	s_waitcnt vmcnt(32)
	s_waitcnt lgkmcnt(0)
	s_barrier
	s_setprio 1
	s_waitcnt lgkmcnt(0)
	v_mfma_f32_16x16x32_bf16 v[124:127], v[140:143], v[176:179], v[124:127]
	v_mfma_f32_16x16x32_bf16 v[120:123], v[148:151], v[176:179], v[120:123]
	v_mfma_f32_16x16x32_bf16 v[108:111], v[140:143], v[184:187], v[108:111]
	v_mfma_f32_16x16x32_bf16 v[104:107], v[148:151], v[184:187], v[104:107]
	v_mfma_f32_16x16x32_bf16 v[92:95], v[140:143], v[192:195], v[92:95]
	v_mfma_f32_16x16x32_bf16 v[88:91], v[148:151], v[192:195], v[88:91]
	v_mfma_f32_16x16x32_bf16 v[76:79], v[140:143], v[200:203], v[76:79]
	v_mfma_f32_16x16x32_bf16 v[72:75], v[148:151], v[200:203], v[72:75]
	v_mfma_f32_16x16x32_bf16 v[124:127], v[144:147], v[180:183], v[124:127]
	v_mfma_f32_16x16x32_bf16 v[120:123], v[152:155], v[180:183], v[120:123]
	v_mfma_f32_16x16x32_bf16 v[108:111], v[144:147], v[188:191], v[108:111]
	v_mfma_f32_16x16x32_bf16 v[104:107], v[152:155], v[188:191], v[104:107]
	v_mfma_f32_16x16x32_bf16 v[92:95], v[144:147], v[196:199], v[92:95]
	v_mfma_f32_16x16x32_bf16 v[88:91], v[152:155], v[196:199], v[88:91]
	v_mfma_f32_16x16x32_bf16 v[76:79], v[144:147], v[204:207], v[76:79]
	v_mfma_f32_16x16x32_bf16 v[72:75], v[152:155], v[204:207], v[72:75]
	s_setprio 0
	s_setprio 1
	v_mfma_f32_16x16x32_bf16 v[116:119], v[156:159], v[176:179], v[116:119]
	v_mfma_f32_16x16x32_bf16 v[112:115], v[168:171], v[176:179], v[112:115]
	v_mfma_f32_16x16x32_bf16 v[100:103], v[156:159], v[184:187], v[100:103]
	v_mfma_f32_16x16x32_bf16 v[96:99], v[168:171], v[184:187], v[96:99]
	v_mfma_f32_16x16x32_bf16 v[84:87], v[156:159], v[192:195], v[84:87]
	v_mfma_f32_16x16x32_bf16 v[80:83], v[168:171], v[192:195], v[80:83]
	v_mfma_f32_16x16x32_bf16 v[68:71], v[156:159], v[200:203], v[68:71]
	v_mfma_f32_16x16x32_bf16 v[64:67], v[168:171], v[200:203], v[64:67]
	v_mfma_f32_16x16x32_bf16 v[116:119], v[160:163], v[180:183], v[116:119]
	v_mfma_f32_16x16x32_bf16 v[112:115], v[172:175], v[180:183], v[112:115]
	v_mfma_f32_16x16x32_bf16 v[100:103], v[160:163], v[188:191], v[100:103]
	v_mfma_f32_16x16x32_bf16 v[96:99], v[172:175], v[188:191], v[96:99]
	v_mfma_f32_16x16x32_bf16 v[84:87], v[160:163], v[196:199], v[84:87]
	v_mfma_f32_16x16x32_bf16 v[80:83], v[172:175], v[196:199], v[80:83]
	v_mfma_f32_16x16x32_bf16 v[68:71], v[160:163], v[204:207], v[68:71]
	v_mfma_f32_16x16x32_bf16 v[64:67], v[172:175], v[204:207], v[64:67]
	s_setprio 0
	s_barrier
	s_add_i32 s68, s57, s33
	s_mov_b32 m0, s68
	ds_read_b128 v[176:179], v164 offset:16384
	ds_read_b128 v[180:183], v164 offset:17408
	ds_read_b128 v[184:187], v164 offset:18432
	ds_read_b128 v[188:191], v164 offset:19456
	ds_read_b128 v[192:195], v164 offset:20480
	ds_read_b128 v[196:199], v164 offset:21504
	ds_read_b128 v[200:203], v164 offset:22528
	ds_read_b128 v[204:207], v164 offset:23552
	global_load_lds_dwordx4 v166, s[44:45]
	s_add_i32 m0, s68, 0x2000
	s_nop 0
	global_load_lds_dwordx4 v134, s[44:45]
	s_add_i32 s44, s60, s33
	s_mov_b32 m0, s44
	s_nop 0
	global_load_lds_dwordx4 v166, s[46:47]
	s_add_i32 m0, s44, 0x2000
	s_nop 0
	global_load_lds_dwordx4 v134, s[46:47]
	s_mov_b32 m0, s38
	s_nop 0
	global_load_lds_dwordx4 v128, s[42:43]
	s_mov_b32 m0, s39
	s_nop 0
	global_load_lds_dwordx4 v132, s[42:43]
	s_waitcnt vmcnt(32)
	s_waitcnt lgkmcnt(0)
	s_barrier
	s_setprio 1
	s_waitcnt lgkmcnt(0)
	v_mfma_f32_16x16x32_bf16 v[60:63], v[140:143], v[176:179], v[60:63]
	v_mfma_f32_16x16x32_bf16 v[56:59], v[148:151], v[176:179], v[56:59]
	v_mfma_f32_16x16x32_bf16 v[44:47], v[140:143], v[184:187], v[44:47]
	v_mfma_f32_16x16x32_bf16 v[40:43], v[148:151], v[184:187], v[40:43]
	v_mfma_f32_16x16x32_bf16 v[28:31], v[140:143], v[192:195], v[28:31]
	v_mfma_f32_16x16x32_bf16 v[24:27], v[148:151], v[192:195], v[24:27]
	v_mfma_f32_16x16x32_bf16 v[12:15], v[140:143], v[200:203], v[12:15]
	v_mfma_f32_16x16x32_bf16 v[8:11], v[148:151], v[200:203], v[8:11]
	v_mfma_f32_16x16x32_bf16 v[60:63], v[144:147], v[180:183], v[60:63]
	v_mfma_f32_16x16x32_bf16 v[56:59], v[152:155], v[180:183], v[56:59]
	v_mfma_f32_16x16x32_bf16 v[44:47], v[144:147], v[188:191], v[44:47]
	v_mfma_f32_16x16x32_bf16 v[40:43], v[152:155], v[188:191], v[40:43]
	v_mfma_f32_16x16x32_bf16 v[28:31], v[144:147], v[196:199], v[28:31]
	v_mfma_f32_16x16x32_bf16 v[24:27], v[152:155], v[196:199], v[24:27]
	v_mfma_f32_16x16x32_bf16 v[12:15], v[144:147], v[204:207], v[12:15]
	v_mfma_f32_16x16x32_bf16 v[8:11], v[152:155], v[204:207], v[8:11]
	s_setprio 0
	s_setprio 1
	v_mfma_f32_16x16x32_bf16 v[52:55], v[156:159], v[176:179], v[52:55]
	v_mfma_f32_16x16x32_bf16 v[48:51], v[168:171], v[176:179], v[48:51]
	v_mfma_f32_16x16x32_bf16 v[36:39], v[156:159], v[184:187], v[36:39]
	v_mfma_f32_16x16x32_bf16 v[32:35], v[168:171], v[184:187], v[32:35]
	v_mfma_f32_16x16x32_bf16 v[20:23], v[156:159], v[192:195], v[20:23]
	v_mfma_f32_16x16x32_bf16 v[16:19], v[168:171], v[192:195], v[16:19]
	v_mfma_f32_16x16x32_bf16 v[4:7], v[156:159], v[200:203], v[4:7]
	v_mfma_f32_16x16x32_bf16 v[0:3], v[168:171], v[200:203], v[0:3]
	v_mfma_f32_16x16x32_bf16 v[52:55], v[160:163], v[180:183], v[52:55]
	v_mfma_f32_16x16x32_bf16 v[48:51], v[172:175], v[180:183], v[48:51]
	v_mfma_f32_16x16x32_bf16 v[36:39], v[160:163], v[188:191], v[36:39]
	v_mfma_f32_16x16x32_bf16 v[32:35], v[172:175], v[188:191], v[32:35]
	v_mfma_f32_16x16x32_bf16 v[20:23], v[160:163], v[196:199], v[20:23]
	v_mfma_f32_16x16x32_bf16 v[16:19], v[172:175], v[196:199], v[16:19]
	v_mfma_f32_16x16x32_bf16 v[4:7], v[160:163], v[204:207], v[4:7]
	v_mfma_f32_16x16x32_bf16 v[0:3], v[172:175], v[204:207], v[0:3]
	s_setprio 0
	s_barrier
; #define PG8_MMA(ai, bj, At, Bt) do { __builtin_amdgcn_s_setprio(1); _Pragma("unroll") for (int m = 0; m < 4; ++m) _Pragma("unroll") for (int n = 0; n < 2; ++n) _Pragma("unroll") for (int k = 0; k < 2; ++k) \
;         acc[ai][bj][m][n] = __builtin_amdgcn_mfma_f32_16x16x32_bf16(Bt[n][k], At[m][k], acc[ai][bj][m][n], 0, 0, 0); __builtin_amdgcn_s_setprio(0); } while (0)
;     ...
;         { const int tmid = (TSW > 0 && TSW < nt) ? TSW : nt;
;           _Pragma("unroll 1") for (int t = 0; t < tmid; t += 2) { PG8_BODY(PG8_MMA) }
	s_add_i32 s42, 0, 0x18000
	v_add_u32_e32 v130, s42, v129
	s_add_i32 s43, 0, 0x1c000
	ds_read_b128 v[140:143], v130
	ds_read_b128 v[144:147], v130 offset:1024
	ds_read_b128 v[148:151], v130 offset:2048
	ds_read_b128 v[152:155], v130 offset:3072
	v_add_u32_e32 v130, s43, v129
	ds_read_b128 v[156:159], v130
	ds_read_b128 v[160:163], v130 offset:1024
	ds_read_b128 v[168:171], v130 offset:2048
	ds_read_b128 v[172:175], v130 offset:3072
	s_mov_b32 m0, s52
	ds_read_b128 v[176:179], v164 offset:32768
	ds_read_b128 v[180:183], v164 offset:33792
	ds_read_b128 v[184:187], v164 offset:34816
	ds_read_b128 v[188:191], v164 offset:35840
	ds_read_b128 v[192:195], v164 offset:36864
	ds_read_b128 v[196:199], v164 offset:37888
	ds_read_b128 v[200:203], v164 offset:38912
	ds_read_b128 v[204:207], v164 offset:39936
	global_load_lds_dwordx4 v128, s[40:41]
	s_mov_b32 m0, s53
	s_nop 0
	global_load_lds_dwordx4 v132, s[40:41]
	s_waitcnt vmcnt(8)
	s_waitcnt lgkmcnt(0)
	s_barrier
	s_setprio 1
	s_waitcnt lgkmcnt(0)
	v_mfma_f32_16x16x32_bf16 v[124:127], v[140:143], v[176:179], v[124:127]
	v_mfma_f32_16x16x32_bf16 v[120:123], v[148:151], v[176:179], v[120:123]
	v_mfma_f32_16x16x32_bf16 v[108:111], v[140:143], v[184:187], v[108:111]
	v_mfma_f32_16x16x32_bf16 v[104:107], v[148:151], v[184:187], v[104:107]
	v_mfma_f32_16x16x32_bf16 v[92:95], v[140:143], v[192:195], v[92:95]
	v_mfma_f32_16x16x32_bf16 v[88:91], v[148:151], v[192:195], v[88:91]
	v_mfma_f32_16x16x32_bf16 v[76:79], v[140:143], v[200:203], v[76:79]
	v_mfma_f32_16x16x32_bf16 v[72:75], v[148:151], v[200:203], v[72:75]
	v_mfma_f32_16x16x32_bf16 v[124:127], v[144:147], v[180:183], v[124:127]
	v_mfma_f32_16x16x32_bf16 v[120:123], v[152:155], v[180:183], v[120:123]
	v_mfma_f32_16x16x32_bf16 v[108:111], v[144:147], v[188:191], v[108:111]
	v_mfma_f32_16x16x32_bf16 v[104:107], v[152:155], v[188:191], v[104:107]
	v_mfma_f32_16x16x32_bf16 v[92:95], v[144:147], v[196:199], v[92:95]
	v_mfma_f32_16x16x32_bf16 v[88:91], v[152:155], v[196:199], v[88:91]
	v_mfma_f32_16x16x32_bf16 v[76:79], v[144:147], v[204:207], v[76:79]
	v_mfma_f32_16x16x32_bf16 v[72:75], v[152:155], v[204:207], v[72:75]
	s_setprio 0
	s_setprio 1
	v_mfma_f32_16x16x32_bf16 v[116:119], v[156:159], v[176:179], v[116:119]
	v_mfma_f32_16x16x32_bf16 v[112:115], v[168:171], v[176:179], v[112:115]
	v_mfma_f32_16x16x32_bf16 v[100:103], v[156:159], v[184:187], v[100:103]
	v_mfma_f32_16x16x32_bf16 v[96:99], v[168:171], v[184:187], v[96:99]
	v_mfma_f32_16x16x32_bf16 v[84:87], v[156:159], v[192:195], v[84:87]
	v_mfma_f32_16x16x32_bf16 v[80:83], v[168:171], v[192:195], v[80:83]
	v_mfma_f32_16x16x32_bf16 v[68:71], v[156:159], v[200:203], v[68:71]
	v_mfma_f32_16x16x32_bf16 v[64:67], v[168:171], v[200:203], v[64:67]
	v_mfma_f32_16x16x32_bf16 v[116:119], v[160:163], v[180:183], v[116:119]
	v_mfma_f32_16x16x32_bf16 v[112:115], v[172:175], v[180:183], v[112:115]
	v_mfma_f32_16x16x32_bf16 v[100:103], v[160:163], v[188:191], v[100:103]
	v_mfma_f32_16x16x32_bf16 v[96:99], v[172:175], v[188:191], v[96:99]
	v_mfma_f32_16x16x32_bf16 v[84:87], v[160:163], v[196:199], v[84:87]
	v_mfma_f32_16x16x32_bf16 v[80:83], v[172:175], v[196:199], v[80:83]
	v_mfma_f32_16x16x32_bf16 v[68:71], v[160:163], v[204:207], v[68:71]
	v_mfma_f32_16x16x32_bf16 v[64:67], v[172:175], v[204:207], v[64:67]
	s_setprio 0
	s_barrier
	s_add_i32 s40, s42, s33
	s_mov_b32 m0, s40
	ds_read_b128 v[176:179], v164 offset:49152
	ds_read_b128 v[180:183], v164 offset:50176
	ds_read_b128 v[184:187], v164 offset:51200
	ds_read_b128 v[188:191], v164 offset:52224
	ds_read_b128 v[192:195], v164 offset:53248
	ds_read_b128 v[196:199], v164 offset:54272
	ds_read_b128 v[200:203], v164 offset:55296
	ds_read_b128 v[204:207], v164 offset:56320
	global_load_lds_dwordx4 v166, s[36:37]
	s_add_i32 m0, s40, 0x2000
	s_nop 0
	global_load_lds_dwordx4 v134, s[36:37]
	s_add_i32 s36, s43, s33
	s_mov_b32 m0, s36
	s_nop 0
	global_load_lds_dwordx4 v166, s[28:29]
	s_add_i32 m0, s36, 0x2000
	s_nop 0
	global_load_lds_dwordx4 v134, s[28:29]
	s_mov_b32 m0, s14
	s_nop 0
	global_load_lds_dwordx4 v128, s[34:35]
	s_mov_b32 m0, s15
	s_nop 0
	global_load_lds_dwordx4 v132, s[34:35]
	s_waitcnt vmcnt(8)
	s_waitcnt lgkmcnt(0)
	s_barrier
	s_setprio 1
	s_waitcnt lgkmcnt(0)
	v_mfma_f32_16x16x32_bf16 v[60:63], v[140:143], v[176:179], v[60:63]
	v_mfma_f32_16x16x32_bf16 v[56:59], v[148:151], v[176:179], v[56:59]
	v_mfma_f32_16x16x32_bf16 v[44:47], v[140:143], v[184:187], v[44:47]
	v_mfma_f32_16x16x32_bf16 v[40:43], v[148:151], v[184:187], v[40:43]
	v_mfma_f32_16x16x32_bf16 v[28:31], v[140:143], v[192:195], v[28:31]
	v_mfma_f32_16x16x32_bf16 v[24:27], v[148:151], v[192:195], v[24:27]
	v_mfma_f32_16x16x32_bf16 v[12:15], v[140:143], v[200:203], v[12:15]
	v_mfma_f32_16x16x32_bf16 v[8:11], v[148:151], v[200:203], v[8:11]
	v_mfma_f32_16x16x32_bf16 v[60:63], v[144:147], v[180:183], v[60:63]
	v_mfma_f32_16x16x32_bf16 v[56:59], v[152:155], v[180:183], v[56:59]
	v_mfma_f32_16x16x32_bf16 v[44:47], v[144:147], v[188:191], v[44:47]
	v_mfma_f32_16x16x32_bf16 v[40:43], v[152:155], v[188:191], v[40:43]
	v_mfma_f32_16x16x32_bf16 v[28:31], v[144:147], v[196:199], v[28:31]
	v_mfma_f32_16x16x32_bf16 v[24:27], v[152:155], v[196:199], v[24:27]
	v_mfma_f32_16x16x32_bf16 v[12:15], v[144:147], v[204:207], v[12:15]
	v_mfma_f32_16x16x32_bf16 v[8:11], v[152:155], v[204:207], v[8:11]
	s_setprio 0
	s_setprio 1
	v_mfma_f32_16x16x32_bf16 v[52:55], v[156:159], v[176:179], v[52:55]
	v_mfma_f32_16x16x32_bf16 v[48:51], v[168:171], v[176:179], v[48:51]
	v_mfma_f32_16x16x32_bf16 v[36:39], v[156:159], v[184:187], v[36:39]
	v_mfma_f32_16x16x32_bf16 v[32:35], v[168:171], v[184:187], v[32:35]
	v_mfma_f32_16x16x32_bf16 v[20:23], v[156:159], v[192:195], v[20:23]
	v_mfma_f32_16x16x32_bf16 v[16:19], v[168:171], v[192:195], v[16:19]
	v_mfma_f32_16x16x32_bf16 v[4:7], v[156:159], v[200:203], v[4:7]
	v_mfma_f32_16x16x32_bf16 v[0:3], v[168:171], v[200:203], v[0:3]
	v_mfma_f32_16x16x32_bf16 v[52:55], v[160:163], v[180:183], v[52:55]
	v_mfma_f32_16x16x32_bf16 v[48:51], v[172:175], v[180:183], v[48:51]
	v_mfma_f32_16x16x32_bf16 v[36:39], v[160:163], v[188:191], v[36:39]
	v_mfma_f32_16x16x32_bf16 v[32:35], v[172:175], v[188:191], v[32:35]
	v_mfma_f32_16x16x32_bf16 v[20:23], v[160:163], v[196:199], v[20:23]
	v_mfma_f32_16x16x32_bf16 v[16:19], v[172:175], v[196:199], v[16:19]
	v_mfma_f32_16x16x32_bf16 v[4:7], v[160:163], v[204:207], v[4:7]
	v_mfma_f32_16x16x32_bf16 v[0:3], v[172:175], v[204:207], v[0:3]
	s_setprio 0
	s_barrier
	s_add_i32 s67, s67, 2
	s_add_u32 s61, s61, 0x100
	s_addc_u32 s66, s66, 0
	s_cmp_gt_u32 s67, 29
	s_mov_b64 s[28:29], s[30:31]

;     __device__ __forceinline__ const char* a(const Unit& u) const { return (const char*)A + (size_t)u.pm * 2 * hA(); }
;     __device__ __forceinline__ const char* b(const Unit& u) const { return (const char*)Bt + (size_t)u.pn * 2 * hB() + (size_t)(u.pm >> gshift) * goff; }
;     __device__ __forceinline__ const char* a(const Unit& u) const { return (const char*)A + (size_t)u.pm * 2 * hA(); }
;     __device__ __forceinline__ const char* b(const Unit& u) const { return (const char*)Bt + (size_t)((u.pn >> 4) * 4096 + (u.pn & 15) * 16) * 1024 * 2 + (size_t)(u.pm >> 1) * 512; }
;     __device__ __forceinline__ const char* a(const Unit&) const { return (const char*)A; }
;     __device__ __forceinline__ const char* b(const Unit& u) const { return (const char*)Bt + ((size_t)(((u.pm >> 4) * 1024 + u.pn * 256) * 16 + (u.pm & 15)) * 512) * 2; }
;     ...
; #pragma unroll
;         for (int a = 0; a < 2; ++a)
; #pragma unroll
;             for (int b = 0; b < 2; ++b)
; #pragma unroll
;                 for (int m = 0; m < 4; ++m)
; #pragma unroll
;                     for (int n = 0; n < 2; ++n) acc[a][b][m][n] = (f32x4){0.f, 0.f, 0.f, 0.f};
;         cur = nxt; cA = nA; cB = nB; ++ui;
.LBB0_715:
	s_ashr_i32 s37, s36, 31
	s_lshl_b64 s[22:23], s[36:37], 20
	s_add_u32 s42, s30, s22
	s_addc_u32 s43, s31, s23
	s_and_b64 s[22:23], s[40:41], exec
	s_cselect_b32 s37, s43, s47
	s_cselect_b32 vcc_lo, s42, s46
	s_ashr_i32 s21, s20, 31
	s_lshl_b64 s[22:23], s[20:21], 20
	s_add_u32 s44, s64, s22
	s_addc_u32 s45, s65, s23
	s_and_b64 s[22:23], s[40:41], exec
	s_cselect_b32 s21, s45, s27
	s_cselect_b32 s86, s44, s26
	s_add_u32 s87, s26, 0x100
	v_mov_b32_e32 v0, 0
	s_addc_u32 s88, s27, 0
	s_mov_b32 s89, -2
	v_mov_b32_e32 v1, v0
	v_mov_b32_e32 v2, v0
	v_mov_b32_e32 v3, v0
	v_mov_b32_e32 v4, v0
	v_mov_b32_e32 v5, v0
	v_mov_b32_e32 v6, v0
	v_mov_b32_e32 v7, v0
	v_mov_b32_e32 v16, v0
	v_mov_b32_e32 v17, v0
	v_mov_b32_e32 v18, v0
	v_mov_b32_e32 v19, v0
	v_mov_b32_e32 v20, v0
	v_mov_b32_e32 v21, v0
	v_mov_b32_e32 v22, v0
	v_mov_b32_e32 v23, v0
	v_mov_b32_e32 v32, v0
	v_mov_b32_e32 v33, v0
	v_mov_b32_e32 v34, v0
	v_mov_b32_e32 v35, v0
	v_mov_b32_e32 v36, v0
	v_mov_b32_e32 v37, v0
	v_mov_b32_e32 v38, v0
	v_mov_b32_e32 v39, v0
	v_mov_b32_e32 v48, v0
	v_mov_b32_e32 v49, v0
	v_mov_b32_e32 v50, v0
	v_mov_b32_e32 v51, v0
	v_mov_b32_e32 v52, v0
	v_mov_b32_e32 v53, v0
	v_mov_b32_e32 v54, v0
	v_mov_b32_e32 v55, v0
	v_mov_b32_e32 v8, v0
	v_mov_b32_e32 v9, v0
	v_mov_b32_e32 v10, v0
	v_mov_b32_e32 v11, v0
	v_mov_b32_e32 v12, v0
	v_mov_b32_e32 v13, v0
	v_mov_b32_e32 v14, v0
	v_mov_b32_e32 v15, v0
	v_mov_b32_e32 v24, v0
	v_mov_b32_e32 v25, v0
	v_mov_b32_e32 v26, v0
	v_mov_b32_e32 v27, v0
	v_mov_b32_e32 v28, v0
	v_mov_b32_e32 v29, v0
	v_mov_b32_e32 v30, v0
	v_mov_b32_e32 v31, v0
	v_mov_b32_e32 v40, v0
	v_mov_b32_e32 v41, v0
	v_mov_b32_e32 v42, v0
	v_mov_b32_e32 v43, v0
	v_mov_b32_e32 v44, v0
	v_mov_b32_e32 v45, v0
	v_mov_b32_e32 v46, v0
	v_mov_b32_e32 v47, v0
	v_mov_b32_e32 v56, v0
	v_mov_b32_e32 v57, v0
	v_mov_b32_e32 v58, v0
	v_mov_b32_e32 v59, v0
	v_mov_b32_e32 v60, v0
	v_mov_b32_e32 v61, v0
	v_mov_b32_e32 v62, v0
	v_mov_b32_e32 v63, v0
	v_mov_b32_e32 v64, v0
	v_mov_b32_e32 v65, v0
	v_mov_b32_e32 v66, v0
	v_mov_b32_e32 v67, v0
	v_mov_b32_e32 v68, v0
	v_mov_b32_e32 v69, v0
	v_mov_b32_e32 v70, v0
	v_mov_b32_e32 v71, v0
	v_mov_b32_e32 v80, v0
	v_mov_b32_e32 v81, v0
	v_mov_b32_e32 v82, v0
	v_mov_b32_e32 v83, v0
	v_mov_b32_e32 v84, v0
	v_mov_b32_e32 v85, v0
	v_mov_b32_e32 v86, v0
	v_mov_b32_e32 v87, v0
	v_mov_b32_e32 v96, v0
	v_mov_b32_e32 v97, v0
	v_mov_b32_e32 v98, v0
	v_mov_b32_e32 v99, v0
	v_mov_b32_e32 v100, v0
	v_mov_b32_e32 v101, v0
	v_mov_b32_e32 v102, v0
	v_mov_b32_e32 v103, v0
	v_mov_b32_e32 v112, v0
	v_mov_b32_e32 v113, v0
	v_mov_b32_e32 v114, v0
	v_mov_b32_e32 v115, v0
	v_mov_b32_e32 v116, v0
	v_mov_b32_e32 v117, v0
	v_mov_b32_e32 v118, v0
	v_mov_b32_e32 v119, v0
	v_mov_b32_e32 v72, v0
	v_mov_b32_e32 v73, v0
	v_mov_b32_e32 v74, v0
	v_mov_b32_e32 v75, v0
	v_mov_b32_e32 v76, v0
	v_mov_b32_e32 v77, v0
	v_mov_b32_e32 v78, v0
	v_mov_b32_e32 v79, v0
	v_mov_b32_e32 v88, v0
	v_mov_b32_e32 v89, v0
	v_mov_b32_e32 v90, v0
	v_mov_b32_e32 v91, v0
	v_mov_b32_e32 v92, v0
	v_mov_b32_e32 v93, v0
	v_mov_b32_e32 v94, v0
	v_mov_b32_e32 v95, v0
	v_mov_b32_e32 v104, v0
	v_mov_b32_e32 v105, v0
	v_mov_b32_e32 v106, v0
	v_mov_b32_e32 v107, v0
	v_mov_b32_e32 v108, v0
	v_mov_b32_e32 v109, v0
	v_mov_b32_e32 v110, v0
	v_mov_b32_e32 v111, v0
	v_mov_b32_e32 v120, v0
	v_mov_b32_e32 v121, v0
	v_mov_b32_e32 v122, v0
	v_mov_b32_e32 v123, v0
	v_mov_b32_e32 v124, v0
	v_mov_b32_e32 v125, v0
	v_mov_b32_e32 v126, v0
	v_mov_b32_e32 v127, v0
	s_cmp_lt_u32 s73, 2
	s_cbranch_scc1 .LBB0_716
	s_add_u32 s80, s46, 0x100
	s_addc_u32 s81, s47, 0
	s_cmp_eq_u32 s89, 28
	s_cselect_b32 s28, vcc_lo, s80
	s_cselect_b32 s29, s37, s81
	s_cselect_b32 s23, s21, s88
	s_cselect_b32 s22, s86, s87
	s_add_u32 s26, s28, 0x80
	s_addc_u32 s27, s29, 0
	s_add_u32 s66, s22, 0x80
	s_addc_u32 s67, s23, 0
	s_add_u32 s90, s46, 0x80080
	s_addc_u32 s91, s47, 0
	s_add_u32 s52, s28, 0x80000
	s_addc_u32 s53, s29, 0
	s_add_u32 s56, s22, 0x80000
	s_addc_u32 s57, s23, 0
	s_add_u32 s46, s22, 0x80080
	s_addc_u32 s47, s23, 0
	s_add_i32 s92, 0, 0x10000
	v_add_u32_e32 v133, s92, v129
	s_add_i32 s93, 0, 0x14000
	ds_read_b128 v[134:137], v133
	ds_read_b128 v[138:141], v133 offset:1024
	ds_read_b128 v[142:145], v133 offset:2048
	ds_read_b128 v[146:149], v133 offset:3072
	v_add_u32_e32 v133, s93, v129
	ds_read_b128 v[150:153], v133
	ds_read_b128 v[154:157], v133 offset:1024
	ds_read_b128 v[158:161], v133 offset:2048
	ds_read_b128 v[162:165], v133 offset:3072
	s_add_i32 m0, s0, 0xc000
	ds_read_b128 v[166:169], v131
	ds_read_b128 v[170:173], v131 offset:1024
	ds_read_b128 v[174:177], v131 offset:2048
	ds_read_b128 v[178:181], v131 offset:3072
	ds_read_b128 v[182:185], v131 offset:4096
	ds_read_b128 v[186:189], v131 offset:5120
	ds_read_b128 v[202:205], v131 offset:6144
	ds_read_b128 v[206:209], v131 offset:7168
	global_load_lds_dwordx4 v128, s[90:91]
	s_add_i32 m0, s0, 0xe000
	s_nop 0
	global_load_lds_dwordx4 v130, s[90:91]
	s_waitcnt vmcnt(32)
	s_waitcnt lgkmcnt(0)
	s_barrier
	s_setprio 1
	s_waitcnt lgkmcnt(0)
	v_mfma_f32_16x16x32_bf16 v[124:127], v[134:137], v[166:169], v[124:127]
	v_mfma_f32_16x16x32_bf16 v[120:123], v[142:145], v[166:169], v[120:123]
	v_mfma_f32_16x16x32_bf16 v[108:111], v[134:137], v[174:177], v[108:111]
	v_mfma_f32_16x16x32_bf16 v[104:107], v[142:145], v[174:177], v[104:107]
	v_mfma_f32_16x16x32_bf16 v[92:95], v[134:137], v[182:185], v[92:95]
	v_mfma_f32_16x16x32_bf16 v[88:91], v[142:145], v[182:185], v[88:91]
	v_mfma_f32_16x16x32_bf16 v[76:79], v[134:137], v[202:205], v[76:79]
	v_mfma_f32_16x16x32_bf16 v[72:75], v[142:145], v[202:205], v[72:75]
	v_mfma_f32_16x16x32_bf16 v[124:127], v[138:141], v[170:173], v[124:127]
	v_mfma_f32_16x16x32_bf16 v[120:123], v[146:149], v[170:173], v[120:123]
	v_mfma_f32_16x16x32_bf16 v[108:111], v[138:141], v[178:181], v[108:111]
	v_mfma_f32_16x16x32_bf16 v[104:107], v[146:149], v[178:181], v[104:107]
	v_mfma_f32_16x16x32_bf16 v[92:95], v[138:141], v[186:189], v[92:95]
	v_mfma_f32_16x16x32_bf16 v[88:91], v[146:149], v[186:189], v[88:91]
	v_mfma_f32_16x16x32_bf16 v[76:79], v[138:141], v[206:209], v[76:79]
	v_mfma_f32_16x16x32_bf16 v[72:75], v[146:149], v[206:209], v[72:75]
	s_setprio 0
	s_setprio 1
	v_mfma_f32_16x16x32_bf16 v[116:119], v[150:153], v[166:169], v[116:119]
	v_mfma_f32_16x16x32_bf16 v[112:115], v[158:161], v[166:169], v[112:115]
	v_mfma_f32_16x16x32_bf16 v[100:103], v[150:153], v[174:177], v[100:103]
	v_mfma_f32_16x16x32_bf16 v[96:99], v[158:161], v[174:177], v[96:99]
	v_mfma_f32_16x16x32_bf16 v[84:87], v[150:153], v[182:185], v[84:87]
	v_mfma_f32_16x16x32_bf16 v[80:83], v[158:161], v[182:185], v[80:83]
	v_mfma_f32_16x16x32_bf16 v[68:71], v[150:153], v[202:205], v[68:71]
	v_mfma_f32_16x16x32_bf16 v[64:67], v[158:161], v[202:205], v[64:67]
	v_mfma_f32_16x16x32_bf16 v[116:119], v[154:157], v[170:173], v[116:119]
	v_mfma_f32_16x16x32_bf16 v[112:115], v[162:165], v[170:173], v[112:115]
	v_mfma_f32_16x16x32_bf16 v[100:103], v[154:157], v[178:181], v[100:103]
	v_mfma_f32_16x16x32_bf16 v[96:99], v[162:165], v[178:181], v[96:99]
	v_mfma_f32_16x16x32_bf16 v[84:87], v[154:157], v[186:189], v[84:87]
	v_mfma_f32_16x16x32_bf16 v[80:83], v[162:165], v[186:189], v[80:83]
	v_mfma_f32_16x16x32_bf16 v[68:71], v[154:157], v[206:209], v[68:71]
	v_mfma_f32_16x16x32_bf16 v[64:67], v[162:165], v[206:209], v[64:67]
	s_setprio 0
	s_barrier
	s_add_i32 s90, s92, s33
	s_mov_b32 m0, s90
	ds_read_b128 v[166:169], v131 offset:16384
	ds_read_b128 v[170:173], v131 offset:17408
	ds_read_b128 v[174:177], v131 offset:18432
	ds_read_b128 v[178:181], v131 offset:19456
	ds_read_b128 v[182:185], v131 offset:20480
	ds_read_b128 v[186:189], v131 offset:21504
	ds_read_b128 v[202:205], v131 offset:22528
	ds_read_b128 v[206:209], v131 offset:23552
	global_load_lds_dwordx4 v192, s[22:23]
	s_add_i32 m0, s90, 0x2000
	s_nop 0
	global_load_lds_dwordx4 v132, s[22:23]
	s_add_i32 s22, s93, s33
	s_mov_b32 m0, s22
	s_nop 0
	global_load_lds_dwordx4 v192, s[56:57]
	s_add_i32 m0, s22, 0x2000
	s_nop 0
	global_load_lds_dwordx4 v132, s[56:57]
	s_mov_b32 m0, s0
	s_nop 0
	global_load_lds_dwordx4 v128, s[28:29]
	s_mov_b32 m0, s1
	s_nop 0
	global_load_lds_dwordx4 v130, s[28:29]
	s_waitcnt vmcnt(32)
	s_waitcnt lgkmcnt(0)
	s_barrier
	s_setprio 1
	s_waitcnt lgkmcnt(0)
	v_mfma_f32_16x16x32_bf16 v[60:63], v[134:137], v[166:169], v[60:63]
	v_mfma_f32_16x16x32_bf16 v[56:59], v[142:145], v[166:169], v[56:59]
	v_mfma_f32_16x16x32_bf16 v[44:47], v[134:137], v[174:177], v[44:47]
	v_mfma_f32_16x16x32_bf16 v[40:43], v[142:145], v[174:177], v[40:43]
	v_mfma_f32_16x16x32_bf16 v[28:31], v[134:137], v[182:185], v[28:31]
	v_mfma_f32_16x16x32_bf16 v[24:27], v[142:145], v[182:185], v[24:27]
	v_mfma_f32_16x16x32_bf16 v[12:15], v[134:137], v[202:205], v[12:15]
	v_mfma_f32_16x16x32_bf16 v[8:11], v[142:145], v[202:205], v[8:11]
	v_mfma_f32_16x16x32_bf16 v[60:63], v[138:141], v[170:173], v[60:63]
	v_mfma_f32_16x16x32_bf16 v[56:59], v[146:149], v[170:173], v[56:59]
	v_mfma_f32_16x16x32_bf16 v[44:47], v[138:141], v[178:181], v[44:47]
	v_mfma_f32_16x16x32_bf16 v[40:43], v[146:149], v[178:181], v[40:43]
	v_mfma_f32_16x16x32_bf16 v[28:31], v[138:141], v[186:189], v[28:31]
	v_mfma_f32_16x16x32_bf16 v[24:27], v[146:149], v[186:189], v[24:27]
	v_mfma_f32_16x16x32_bf16 v[12:15], v[138:141], v[206:209], v[12:15]
	v_mfma_f32_16x16x32_bf16 v[8:11], v[146:149], v[206:209], v[8:11]
	s_setprio 0
	s_setprio 1
	v_mfma_f32_16x16x32_bf16 v[52:55], v[150:153], v[166:169], v[52:55]
	v_mfma_f32_16x16x32_bf16 v[48:51], v[158:161], v[166:169], v[48:51]
	v_mfma_f32_16x16x32_bf16 v[36:39], v[150:153], v[174:177], v[36:39]
	v_mfma_f32_16x16x32_bf16 v[32:35], v[158:161], v[174:177], v[32:35]
	v_mfma_f32_16x16x32_bf16 v[20:23], v[150:153], v[182:185], v[20:23]
	v_mfma_f32_16x16x32_bf16 v[16:19], v[158:161], v[182:185], v[16:19]
	v_mfma_f32_16x16x32_bf16 v[4:7], v[150:153], v[202:205], v[4:7]
	v_mfma_f32_16x16x32_bf16 v[0:3], v[158:161], v[202:205], v[0:3]
	v_mfma_f32_16x16x32_bf16 v[52:55], v[154:157], v[170:173], v[52:55]
	v_mfma_f32_16x16x32_bf16 v[48:51], v[162:165], v[170:173], v[48:51]
	v_mfma_f32_16x16x32_bf16 v[36:39], v[154:157], v[178:181], v[36:39]
	v_mfma_f32_16x16x32_bf16 v[32:35], v[162:165], v[178:181], v[32:35]
	v_mfma_f32_16x16x32_bf16 v[20:23], v[154:157], v[186:189], v[20:23]
	v_mfma_f32_16x16x32_bf16 v[16:19], v[162:165], v[186:189], v[16:19]
	v_mfma_f32_16x16x32_bf16 v[4:7], v[154:157], v[206:209], v[4:7]
	v_mfma_f32_16x16x32_bf16 v[0:3], v[162:165], v[206:209], v[0:3]
	s_setprio 0
	s_barrier
; #define PG8_MMA(ai, bj, At, Bt) do { __builtin_amdgcn_s_setprio(1); _Pragma("unroll") for (int m = 0; m < 4; ++m) _Pragma("unroll") for (int n = 0; n < 2; ++n) _Pragma("unroll") for (int k = 0; k < 2; ++k) \
;         acc[ai][bj][m][n] = __builtin_amdgcn_mfma_f32_16x16x32_bf16(Bt[n][k], At[m][k], acc[ai][bj][m][n], 0, 0, 0); __builtin_amdgcn_s_setprio(0); } while (0)
;     ...
;         { const int tmid = (TSW > 0 && TSW < nt) ? TSW : nt;
;           _Pragma("unroll 1") for (int t = 0; t < tmid; t += 2) { PG8_BODY(PG8_MMA) }
	s_add_i32 s22, 0, 0x18000
	v_add_u32_e32 v133, s22, v129
	s_add_i32 s23, 0, 0x1c000
	ds_read_b128 v[134:137], v133
	ds_read_b128 v[138:141], v133 offset:1024
	ds_read_b128 v[142:145], v133 offset:2048
	ds_read_b128 v[146:149], v133 offset:3072
	v_add_u32_e32 v133, s23, v129
	ds_read_b128 v[150:153], v133
	ds_read_b128 v[154:157], v133 offset:1024
	ds_read_b128 v[158:161], v133 offset:2048
	ds_read_b128 v[162:165], v133 offset:3072
	s_mov_b32 m0, s34
	ds_read_b128 v[166:169], v131 offset:32768
	ds_read_b128 v[170:173], v131 offset:33792
	ds_read_b128 v[174:177], v131 offset:34816
	ds_read_b128 v[178:181], v131 offset:35840
	ds_read_b128 v[182:185], v131 offset:36864
	ds_read_b128 v[186:189], v131 offset:37888
	ds_read_b128 v[202:205], v131 offset:38912
	ds_read_b128 v[206:209], v131 offset:39936
	global_load_lds_dwordx4 v128, s[52:53]
	s_mov_b32 m0, s35
	s_nop 0
	global_load_lds_dwordx4 v130, s[52:53]
	s_waitcnt vmcnt(8)
	s_waitcnt lgkmcnt(0)
	s_barrier
	s_setprio 1
	s_waitcnt lgkmcnt(0)
	v_mfma_f32_16x16x32_bf16 v[124:127], v[134:137], v[166:169], v[124:127]
	v_mfma_f32_16x16x32_bf16 v[120:123], v[142:145], v[166:169], v[120:123]
	v_mfma_f32_16x16x32_bf16 v[108:111], v[134:137], v[174:177], v[108:111]
	v_mfma_f32_16x16x32_bf16 v[104:107], v[142:145], v[174:177], v[104:107]
	v_mfma_f32_16x16x32_bf16 v[92:95], v[134:137], v[182:185], v[92:95]
	v_mfma_f32_16x16x32_bf16 v[88:91], v[142:145], v[182:185], v[88:91]
	v_mfma_f32_16x16x32_bf16 v[76:79], v[134:137], v[202:205], v[76:79]
	v_mfma_f32_16x16x32_bf16 v[72:75], v[142:145], v[202:205], v[72:75]
	v_mfma_f32_16x16x32_bf16 v[124:127], v[138:141], v[170:173], v[124:127]
	v_mfma_f32_16x16x32_bf16 v[120:123], v[146:149], v[170:173], v[120:123]
	v_mfma_f32_16x16x32_bf16 v[108:111], v[138:141], v[178:181], v[108:111]
	v_mfma_f32_16x16x32_bf16 v[104:107], v[146:149], v[178:181], v[104:107]
	v_mfma_f32_16x16x32_bf16 v[92:95], v[138:141], v[186:189], v[92:95]
	v_mfma_f32_16x16x32_bf16 v[88:91], v[146:149], v[186:189], v[88:91]
	v_mfma_f32_16x16x32_bf16 v[76:79], v[138:141], v[206:209], v[76:79]
	v_mfma_f32_16x16x32_bf16 v[72:75], v[146:149], v[206:209], v[72:75]
	s_setprio 0
	s_setprio 1
	v_mfma_f32_16x16x32_bf16 v[116:119], v[150:153], v[166:169], v[116:119]
	v_mfma_f32_16x16x32_bf16 v[112:115], v[158:161], v[166:169], v[112:115]
	v_mfma_f32_16x16x32_bf16 v[100:103], v[150:153], v[174:177], v[100:103]
	v_mfma_f32_16x16x32_bf16 v[96:99], v[158:161], v[174:177], v[96:99]
	v_mfma_f32_16x16x32_bf16 v[84:87], v[150:153], v[182:185], v[84:87]
	v_mfma_f32_16x16x32_bf16 v[80:83], v[158:161], v[182:185], v[80:83]
	v_mfma_f32_16x16x32_bf16 v[68:71], v[150:153], v[202:205], v[68:71]
	v_mfma_f32_16x16x32_bf16 v[64:67], v[158:161], v[202:205], v[64:67]
	v_mfma_f32_16x16x32_bf16 v[116:119], v[154:157], v[170:173], v[116:119]
	v_mfma_f32_16x16x32_bf16 v[112:115], v[162:165], v[170:173], v[112:115]
	v_mfma_f32_16x16x32_bf16 v[100:103], v[154:157], v[178:181], v[100:103]
	v_mfma_f32_16x16x32_bf16 v[96:99], v[162:165], v[178:181], v[96:99]
	v_mfma_f32_16x16x32_bf16 v[84:87], v[154:157], v[186:189], v[84:87]
	v_mfma_f32_16x16x32_bf16 v[80:83], v[162:165], v[186:189], v[80:83]
	v_mfma_f32_16x16x32_bf16 v[68:71], v[154:157], v[206:209], v[68:71]
	v_mfma_f32_16x16x32_bf16 v[64:67], v[162:165], v[206:209], v[64:67]
	s_setprio 0
	s_barrier
	s_add_i32 s22, s22, s33
	s_mov_b32 m0, s22
	ds_read_b128 v[166:169], v131 offset:49152
	ds_read_b128 v[170:173], v131 offset:50176
	ds_read_b128 v[174:177], v131 offset:51200
	ds_read_b128 v[178:181], v131 offset:52224
	ds_read_b128 v[182:185], v131 offset:53248
	ds_read_b128 v[186:189], v131 offset:54272
	ds_read_b128 v[202:205], v131 offset:55296
	ds_read_b128 v[206:209], v131 offset:56320
	global_load_lds_dwordx4 v192, s[66:67]
	s_add_i32 m0, s22, 0x2000
	s_add_i32 s22, s23, s33
	global_load_lds_dwordx4 v132, s[66:67]
	s_mov_b32 m0, s22
	s_nop 0
	global_load_lds_dwordx4 v192, s[46:47]
	s_add_i32 m0, s22, 0x2000
	s_nop 0
	global_load_lds_dwordx4 v132, s[46:47]
	s_mov_b32 m0, s54
	s_nop 0
	global_load_lds_dwordx4 v128, s[26:27]
	s_mov_b32 m0, s55
	s_nop 0
	global_load_lds_dwordx4 v130, s[26:27]
	s_waitcnt vmcnt(8)
	s_waitcnt lgkmcnt(0)
	s_barrier
	s_setprio 1
	s_waitcnt lgkmcnt(0)
	v_mfma_f32_16x16x32_bf16 v[60:63], v[134:137], v[166:169], v[60:63]
	v_mfma_f32_16x16x32_bf16 v[56:59], v[142:145], v[166:169], v[56:59]
	v_mfma_f32_16x16x32_bf16 v[44:47], v[134:137], v[174:177], v[44:47]
	v_mfma_f32_16x16x32_bf16 v[40:43], v[142:145], v[174:177], v[40:43]
	v_mfma_f32_16x16x32_bf16 v[28:31], v[134:137], v[182:185], v[28:31]
	v_mfma_f32_16x16x32_bf16 v[24:27], v[142:145], v[182:185], v[24:27]
	v_mfma_f32_16x16x32_bf16 v[12:15], v[134:137], v[202:205], v[12:15]
	v_mfma_f32_16x16x32_bf16 v[8:11], v[142:145], v[202:205], v[8:11]
	v_mfma_f32_16x16x32_bf16 v[60:63], v[138:141], v[170:173], v[60:63]
	v_mfma_f32_16x16x32_bf16 v[56:59], v[146:149], v[170:173], v[56:59]
	v_mfma_f32_16x16x32_bf16 v[44:47], v[138:141], v[178:181], v[44:47]
	v_mfma_f32_16x16x32_bf16 v[40:43], v[146:149], v[178:181], v[40:43]
	v_mfma_f32_16x16x32_bf16 v[28:31], v[138:141], v[186:189], v[28:31]
	v_mfma_f32_16x16x32_bf16 v[24:27], v[146:149], v[186:189], v[24:27]
	v_mfma_f32_16x16x32_bf16 v[12:15], v[138:141], v[206:209], v[12:15]
	v_mfma_f32_16x16x32_bf16 v[8:11], v[146:149], v[206:209], v[8:11]
	s_setprio 0
	s_setprio 1
	v_mfma_f32_16x16x32_bf16 v[52:55], v[150:153], v[166:169], v[52:55]
	v_mfma_f32_16x16x32_bf16 v[48:51], v[158:161], v[166:169], v[48:51]
	v_mfma_f32_16x16x32_bf16 v[36:39], v[150:153], v[174:177], v[36:39]
	v_mfma_f32_16x16x32_bf16 v[32:35], v[158:161], v[174:177], v[32:35]
	v_mfma_f32_16x16x32_bf16 v[20:23], v[150:153], v[182:185], v[20:23]
	v_mfma_f32_16x16x32_bf16 v[16:19], v[158:161], v[182:185], v[16:19]
	v_mfma_f32_16x16x32_bf16 v[4:7], v[150:153], v[202:205], v[4:7]
	v_mfma_f32_16x16x32_bf16 v[0:3], v[158:161], v[202:205], v[0:3]
	v_mfma_f32_16x16x32_bf16 v[52:55], v[154:157], v[170:173], v[52:55]
	v_mfma_f32_16x16x32_bf16 v[48:51], v[162:165], v[170:173], v[48:51]
	v_mfma_f32_16x16x32_bf16 v[36:39], v[154:157], v[178:181], v[36:39]
	v_mfma_f32_16x16x32_bf16 v[32:35], v[162:165], v[178:181], v[32:35]
	v_mfma_f32_16x16x32_bf16 v[20:23], v[154:157], v[186:189], v[20:23]
	v_mfma_f32_16x16x32_bf16 v[16:19], v[162:165], v[186:189], v[16:19]
	v_mfma_f32_16x16x32_bf16 v[4:7], v[154:157], v[206:209], v[4:7]
	v_mfma_f32_16x16x32_bf16 v[0:3], v[162:165], v[206:209], v[0:3]
	s_setprio 0
	s_barrier
	s_add_i32 s89, s89, 2
	s_add_u32 s87, s87, 0x100
	s_addc_u32 s88, s88, 0
	s_cmp_gt_u32 s89, 29
	s_mov_b64 s[46:47], s[80:81]
